# speedup vs baseline: 1.0052x; 1.0052x over previous
.LBB0_601:
	s_or_b64 exec, exec, s[0:1]
	s_bfe_u32 s98, s70, 0x20001
	s_cmp_eq_u32 s98, 0
	s_cbranch_scc1 .Lxs_done0
.Lxs_loop0:
	s_sleep 45
	s_sub_u32 s98, s98, 1
	s_cmp_lg_u32 s98, 0
	s_cbranch_scc1 .Lxs_loop0
.Lxs_done0:
	v_mov_b32_e32 v220, v218
	s_cmpk_lt_i32 s70, 0x200
	s_waitcnt lgkmcnt(0)
	s_barrier
	s_cselect_b64 s[10:11], -1, 0
	s_cmpk_gt_i32 s70, 0x1ff
	v_readfirstlane_b32 s12, v220
	s_cbranch_scc1 .LBB0_604
	s_and_b32 s99, s70, 1
	s_lshl_b32 s99, s99, 8
	s_add_i32 s99, s99, s70
	s_ashr_i32 s0, s99, 31
	s_lshr_b32 s0, s0, 29
	s_add_i32 s2, s99, s0
	s_and_b32 s0, s2, -8
	s_sub_i32 s3, s99, s0
	s_cmp_gt_i32 s3, -1
	s_cbranch_scc0 .LBB0_605
	s_lshl_b32 s4, s3, 6
	s_cbranch_execz .LBB0_606
	s_branch .LBB0_607

.Lxs_done1:
	v_mov_b32_e32 v154, v218
	s_waitcnt lgkmcnt(0)
	s_barrier
	s_and_b64 vcc, exec, s[8:9]
	v_readfirstlane_b32 s7, v154
	s_cbranch_vccnz .LBB0_1088
	s_and_b32 s99, s70, 1
	s_lshl_b32 s99, s99, 8
	s_add_i32 s99, s99, s70
	s_ashr_i32 s0, s99, 31
	s_lshr_b32 s0, s0, 29
	s_add_i32 s4, s99, s0
	s_and_b32 s0, s4, -8
	s_sub_i32 s2, s99, s0
	s_cmp_gt_i32 s2, -1
	s_cbranch_scc0 .LBB0_1067
	s_lshl_b32 s3, s2, 6
	s_ashr_i32 s0, s4, 3
	s_cbranch_execz .LBB0_1068
	s_branch .LBB0_1069
